# placement: second loop half moved by 48 bytes (12 nops after the mid-loop barrier), otherwise the session-best file
# speedup vs baseline: 1.0057x; 1.0057x over previous
; #define SBAR() __builtin_amdgcn_sched_barrier(0)
; #define RESC(a) do { if (__any((a) < 1.f)) { if (hi == 0) al_l[r32] = (a); asm volatile("s_waitcnt lgkmcnt(0)" ::: "memory"); \
;     for (int d = 0; d < 4; ++d) for (int r = 0; r < 16; ++r) o[d][r] *= al_l[crow(r, hi)]; } } while (0)
; __device__ __forceinline__ void partialSM(f32x16& p0, f32x16& p1, float& m_reg, float& mn, float& alpha) {
;     ...
;   for (int r = 0; r < 16; ++r) p0[r] = fmaf(p0[r], C, mnC); for (int r = 0; r < 16; ++r) p1[r] = fmaf(p1[r], C, mnC);
;   for (int r = 0; r < 16; ++r) p0[r] = __builtin_amdgcn_exp2f(p0[r]);
; }
; __device__ __forceinline__ void finishSM(f32x16& p0, f32x16& p1, float alpha, float& l_reg, bf16x8& pa0, bf16x8& pa1, bf16x8& pa2, bf16x8& pa3) {
;   for (int r = 0; r < 16; ++r) p1[r] = __builtin_amdgcn_exp2f(p1[r]);
;   float ps = 0; for (int r = 0; r < 16; ++r) ps += p0[r]; for (int r = 0; r < 16; ++r) ps += p1[r];
;   { auto rr = __builtin_amdgcn_permlane32_swap(__float_as_uint(ps), __float_as_uint(ps), false, false);
;     ps = __uint_as_float(rr[0]) + __uint_as_float(rr[1]); }
;   l_reg = l_reg * alpha + ps;
;     ...
;   PK4(p0, 0, pa0); PK4(p0, 8, pa1); PK4(p1, 0, pa2); PK4(p1, 8, pa3);
;     ...
; }
; __device__ __forceinline__ void qkt(f32x16& p0, f32x16& p1, const bf16* Ks, const bf16x8* qr, int r32, int hi) {
;   p0 = f32x16{}; p1 = f32x16{};
;   for (int d0 = 0; d0 < 8; ++d0) { int cb = (d0 * 16 + hi * 8) * 2;
;     bf16x8 b0 = *reinterpret_cast<const bf16x8*>((const char*)Ks + KSWZ(r32, cb));
;     bf16x8 b1 = *reinterpret_cast<const bf16x8*>((const char*)Ks + KSWZ(32 + r32, cb));
;     p0 = __builtin_amdgcn_mfma_f32_32x32x16_bf16(b0, qr[d0], p0, 0, 0, 0);
;     p1 = __builtin_amdgcn_mfma_f32_32x32x16_bf16(b1, qr[d0], p1, 0, 0, 0); }
; template <typename TQ>
; __device__ __forceinline__ void attn_dense_body(const TQ* __restrict__ Qb, const bf16* __restrict__ Kh, const bf16* __restrict__ Vh,
;                                                 unsigned short* __restrict__ Ob, int seq, char* lds) {
;     ...
;     RESC(alB); __syncthreads();
;     SBAR(); qkt(pA0, pA1, K_lds, qr, r32, hi);
;     finishSM(pB0, pB1, alB, l_reg, pa0, pa1, pa2, pa3); SBAR();
.LBB0_1590:
	v_exp_f32_e32 v143, v82
	v_exp_f32_e32 v145, v83
	v_exp_f32_e32 v141, v84
	v_exp_f32_e32 v144, v85
	v_exp_f32_e32 v140, v86
	v_exp_f32_e32 v142, v87
	v_exp_f32_e32 v138, v88
	v_exp_f32_e32 v139, v89
	v_exp_f32_e32 v135, v90
	v_exp_f32_e32 v137, v91
	v_exp_f32_e32 v134, v92
	v_exp_f32_e32 v136, v93
	v_exp_f32_e32 v131, v94
	v_exp_f32_e32 v133, v95
	v_exp_f32_e32 v130, v96
	v_exp_f32_e32 v132, v97
	v_fmamk_f32 v217, v66, 0x3e0293ee, v162
	v_fmamk_f32 v218, v67, 0x3e0293ee, v162
	v_fmamk_f32 v219, v68, 0x3e0293ee, v162
	v_fmamk_f32 v220, v69, 0x3e0293ee, v162
	v_fmamk_f32 v221, v70, 0x3e0293ee, v162
	v_fmamk_f32 v208, v71, 0x3e0293ee, v162
	v_fmamk_f32 v211, v72, 0x3e0293ee, v162
	v_fmamk_f32 v212, v73, 0x3e0293ee, v162
	v_fmamk_f32 v213, v74, 0x3e0293ee, v162
	v_fmamk_f32 v214, v75, 0x3e0293ee, v162
	v_fmamk_f32 v215, v76, 0x3e0293ee, v162
	v_fmamk_f32 v216, v77, 0x3e0293ee, v162
	v_fmamk_f32 v165, v78, 0x3e0293ee, v162
	v_fmamk_f32 v222, v79, 0x3e0293ee, v162
	v_fmamk_f32 v223, v80, 0x3e0293ee, v162
	v_fmac_f32_e32 v162, 0x3e0293ee, v81
	s_waitcnt lgkmcnt(0)
	s_barrier
	s_nop 0
	s_nop 0
	s_nop 0
	s_nop 0
	s_nop 0
	s_nop 0
	s_nop 0
	s_nop 0
	s_nop 0
	s_nop 0
	s_nop 0
	s_nop 0
	ds_read_b128 v[66:69], v195 offset:32768
	ds_read_b128 v[70:73], v195 offset:40960
	ds_read_b128 v[224:227], v196 offset:32768
	ds_read_b128 v[228:231], v196 offset:40960
	v_exp_f32_e32 v235, v165
	v_add_f32_e32 v165, 0, v143
	v_add_f32_e32 v165, v145, v165
	v_add_f32_e32 v165, v141, v165
	v_add_f32_e32 v165, v144, v165
	s_waitcnt lgkmcnt(3)
	v_mfma_f32_32x32x16_bf16 v[82:97], v[66:69], v[126:129], 0
	v_add_f32_e32 v165, v140, v165
	v_add_f32_e32 v165, v142, v165
	v_add_f32_e32 v165, v138, v165
	v_add_f32_e32 v165, v139, v165
	v_add_f32_e32 v165, v135, v165
	s_waitcnt lgkmcnt(2)
	v_mfma_f32_32x32x16_bf16 v[66:81], v[70:73], v[126:129], 0
	v_add_f32_e32 v165, v137, v165
	v_add_f32_e32 v165, v134, v165
	v_add_f32_e32 v165, v136, v165
	v_add_f32_e32 v165, v131, v165
	v_add_f32_e32 v165, v133, v165
	s_waitcnt lgkmcnt(1)
	v_mfma_f32_32x32x16_bf16 v[82:97], v[224:227], v[122:125], v[82:97]
	v_add_f32_e32 v165, v130, v165
	v_add_f32_e32 v165, v132, v165
	v_exp_f32_e32 v208, v208
	v_exp_f32_e32 v232, v214
	v_exp_f32_e32 v233, v215
	s_waitcnt lgkmcnt(0)
	v_mfma_f32_32x32x16_bf16 v[66:81], v[228:231], v[122:125], v[66:81]
	ds_read_b128 v[224:227], v197 offset:32768
	ds_read_b128 v[228:231], v197 offset:40960
	v_exp_f32_e32 v234, v216
	v_exp_f32_e32 v236, v222
	v_exp_f32_e32 v237, v223
	v_exp_f32_e32 v162, v162
	v_exp_f32_e32 v238, v217
	s_waitcnt lgkmcnt(1)
	v_mfma_f32_32x32x16_bf16 v[82:97], v[224:227], v[118:121], v[82:97]
	v_exp_f32_e32 v239, v218
	v_exp_f32_e32 v240, v219
	v_exp_f32_e32 v241, v220
	v_add_f32_e32 v165, v238, v165
	v_add_f32_e32 v165, v239, v165
	s_waitcnt lgkmcnt(0)
	v_mfma_f32_32x32x16_bf16 v[66:81], v[228:231], v[118:121], v[66:81]
	ds_read_b128 v[224:227], v198 offset:32768
	ds_read_b128 v[228:231], v198 offset:40960
	v_add_f32_e32 v165, v240, v165
	v_exp_f32_e32 v242, v221
	v_exp_f32_e32 v243, v211
	v_exp_f32_e32 v244, v212
	v_add_f32_e32 v165, v241, v165
	s_waitcnt lgkmcnt(1)
	v_mfma_f32_32x32x16_bf16 v[82:97], v[224:227], v[114:117], v[82:97]
	v_exp_f32_e32 v245, v213
	v_add_f32_e32 v165, v242, v165
	v_add_f32_e32 v165, v208, v165
	v_add_f32_e32 v165, v243, v165
	v_add_f32_e32 v165, v244, v165
	s_waitcnt lgkmcnt(0)
	v_mfma_f32_32x32x16_bf16 v[66:81], v[228:231], v[114:117], v[66:81]
	ds_read_b128 v[224:227], v199 offset:32768
	ds_read_b128 v[228:231], v199 offset:40960
	v_add_f32_e32 v165, v245, v165
	v_add_f32_e32 v165, v232, v165
	v_add_f32_e32 v165, v233, v165
	v_add_f32_e32 v165, v234, v165
	v_add_f32_e32 v165, v235, v165
	s_waitcnt lgkmcnt(1)
	v_mfma_f32_32x32x16_bf16 v[82:97], v[224:227], v[110:113], v[82:97]
	v_add_f32_e32 v165, v236, v165
	v_add_f32_e32 v165, v237, v165
	v_add_f32_e32 v165, v162, v165
	v_mov_b32_e32 v211, v165
	s_nop 1
	v_permlane32_swap_b32_e32 v165, v211
	s_waitcnt lgkmcnt(0)
	v_mfma_f32_32x32x16_bf16 v[66:81], v[228:231], v[110:113], v[66:81]
	ds_read_b128 v[224:227], v200 offset:32768
	ds_read_b128 v[228:231], v200 offset:40960
	v_cvt_pk_bf16_f32 v212, v143, v145
	v_cvt_pk_bf16_f32 v213, v141, v144
	v_cvt_pk_bf16_f32 v214, v140, v142
	v_cvt_pk_bf16_f32 v215, v138, v139
	v_cvt_pk_bf16_f32 v216, v135, v137
	s_waitcnt lgkmcnt(1)
	v_mfma_f32_32x32x16_bf16 v[82:97], v[224:227], v[106:109], v[82:97]
	v_cvt_pk_bf16_f32 v217, v134, v136
	v_cvt_pk_bf16_f32 v218, v131, v133
	v_cvt_pk_bf16_f32 v219, v130, v132
	v_cvt_pk_bf16_f32 v220, v238, v239
	v_cvt_pk_bf16_f32 v221, v240, v241
	s_waitcnt lgkmcnt(0)
	v_mfma_f32_32x32x16_bf16 v[66:81], v[228:231], v[106:109], v[66:81]
	ds_read_b128 v[224:227], v201 offset:32768
	ds_read_b128 v[228:231], v201 offset:40960
	v_cvt_pk_bf16_f32 v222, v242, v208
	v_cvt_pk_bf16_f32 v223, v243, v244
	v_cvt_pk_bf16_f32 v248, v245, v232
	v_cvt_pk_bf16_f32 v249, v233, v234
	v_cvt_pk_bf16_f32 v250, v235, v236
	s_waitcnt lgkmcnt(1)
	v_mfma_f32_32x32x16_bf16 v[82:97], v[224:227], v[102:105], v[82:97]
	v_cvt_pk_bf16_f32 v251, v237, v162
	s_nop 0
	v_permlane32_swap_b32_e32 v212, v214
	v_permlane32_swap_b32_e32 v213, v215
	v_permlane32_swap_b32_e32 v216, v218
	v_permlane32_swap_b32_e32 v217, v219
	s_waitcnt lgkmcnt(0)
	v_mfma_f32_32x32x16_bf16 v[66:81], v[228:231], v[102:105], v[66:81]
	ds_read_b128 v[224:227], v202 offset:32768
	ds_read_b128 v[228:231], v202 offset:40960
	v_permlane32_swap_b32_e32 v220, v222
	v_permlane32_swap_b32_e32 v221, v223
	v_permlane32_swap_b32_e32 v248, v250
	v_permlane32_swap_b32_e32 v249, v251
	s_waitcnt lgkmcnt(1)
	v_mfma_f32_32x32x16_bf16 v[82:97], v[224:227], v[98:101], v[82:97]
	s_waitcnt lgkmcnt(0)
; __device__ __forceinline__ void partialSM(f32x16& p0, f32x16& p1, float& m_reg, float& mn, float& alpha) {
;   constexpr float C = SCALE * 1.4426950408889634f;
;   float pmax = p0[0]; for (int r = 1; r < 16; ++r) pmax = fmaxf(pmax, p0[r]); for (int r = 0; r < 16; ++r) pmax = fmaxf(pmax, p1[r]);
;   { auto rr = __builtin_amdgcn_permlane32_swap(__float_as_uint(pmax), __float_as_uint(pmax), false, false);
;     pmax = fmaxf(__uint_as_float(rr[0]), __uint_as_float(rr[1])); }
;   if (__builtin_expect(__all(pmax - m_reg <= THR / SCALE), 1)) { mn = m_reg; alpha = 1.f; }
;   else { mn = fmaxf(m_reg, pmax); alpha = __builtin_amdgcn_exp2f((m_reg - mn) * C); m_reg = mn; }
;   float mnC = -mn * C;
;   for (int r = 0; r < 16; ++r) p0[r] = fmaf(p0[r], C, mnC); for (int r = 0; r < 16; ++r) p1[r] = fmaf(p1[r], C, mnC);
;   for (int r = 0; r < 16; ++r) p0[r] = __builtin_amdgcn_exp2f(p0[r]);
; }
; __device__ __forceinline__ void finishSM(f32x16& p0, f32x16& p1, float alpha, float& l_reg, bf16x8& pa0, bf16x8& pa1, bf16x8& pa2, bf16x8& pa3) {
;   for (int r = 0; r < 16; ++r) p1[r] = __builtin_amdgcn_exp2f(p1[r]);
;   float ps = 0; for (int r = 0; r < 16; ++r) ps += p0[r]; for (int r = 0; r < 16; ++r) ps += p1[r];
;   { auto rr = __builtin_amdgcn_permlane32_swap(__float_as_uint(ps), __float_as_uint(ps), false, false);
;     ps = __uint_as_float(rr[0]) + __uint_as_float(rr[1]); }
;   l_reg = l_reg * alpha + ps;
;     ...
;   PK4(p0, 0, pa0); PK4(p0, 8, pa1); PK4(p1, 0, pa2); PK4(p1, 8, pa3);
;     ...
; }
; __device__ __forceinline__ void qkt(f32x16& p0, f32x16& p1, const bf16* Ks, const bf16x8* qr, int r32, int hi) {
;   p0 = f32x16{}; p1 = f32x16{};
;   for (int d0 = 0; d0 < 8; ++d0) { int cb = (d0 * 16 + hi * 8) * 2;
;     bf16x8 b0 = *reinterpret_cast<const bf16x8*>((const char*)Ks + KSWZ(r32, cb));
;     bf16x8 b1 = *reinterpret_cast<const bf16x8*>((const char*)Ks + KSWZ(32 + r32, cb));
;     p0 = __builtin_amdgcn_mfma_f32_32x32x16_bf16(b0, qr[d0], p0, 0, 0, 0);
;     p1 = __builtin_amdgcn_mfma_f32_32x32x16_bf16(b1, qr[d0], p1, 0, 0, 0); }
; }
; __device__ __forceinline__ int v_st(int k, int c) { const int kk = (k & ~0xC) | ((k & 4) << 1) | ((k & 8) >> 1); return ((kk >> 3) * 4 + (c >> 5)) * 512 + ((kk & 7) * 32 + (c & 31)) * 2; }
; __device__ __forceinline__ int v_rd_base(int lane) { return ((lane & 3) << 3) | (((lane >> 2) & 3) << 6) | (((lane >> 4) & 1) << 5) | (((lane >> 5) & 1) << 8); }
	v_mfma_f32_32x32x16_bf16 v[66:81], v[228:231], v[98:101], v[66:81]
	s_cmpk_gt_u32 s68, 0x80
	s_cselect_b64 s[40:41], -1, 0
	s_cmpk_lt_u32 s68, 0x81
	s_cselect_b32 s4, s67, 0x20c0
	v_or_b32_e32 v130, s4, v181
	v_lshl_or_b32 v134, v130, 8, v183
	v_add_u32_e32 v130, s4, v184
	v_lshl_or_b32 v138, v130, 8, v183
	global_load_dwordx4 v[130:133], v134, s[36:37]
	s_nop 0
	global_load_dwordx4 v[134:137], v134, s[34:35]
	s_nop 0
	global_load_dwordx4 v[142:145], v138, s[36:37]
	s_nop 0
	global_load_dwordx4 v[138:141], v138, s[34:35]
	ds_read_b64_tr_b16 v[228:229], v188 offset:0
	ds_read_b64_tr_b16 v[230:231], v188 offset:0x800
	ds_read_b64_tr_b16 v[232:233], v188 offset:0x1000
	ds_read_b64_tr_b16 v[234:235], v188 offset:0x1800
	ds_read_b64_tr_b16 v[236:237], v188 offset:0x2000
	ds_read_b64_tr_b16 v[238:239], v188 offset:0x2800
	ds_read_b64_tr_b16 v[240:241], v188 offset:0x3000
	ds_read_b64_tr_b16 v[242:243], v188 offset:0x3800
	s_waitcnt lgkmcnt(0)
	s_nop 0
	v_mfma_f32_32x32x16_bf16 v[2:17], v[212:215], v[228:231], v[2:17]
	v_max_f32_e32 v224, v83, v83
	v_max_f32_e32 v225, v82, v82
	v_max_f32_e32 v224, v225, v224
	v_max3_f32 v224, v224, v84, v85
	v_max3_f32 v224, v224, v86, v87
	ds_read_b64_tr_b16 v[228:229], v188 offset:0x200
	ds_read_b64_tr_b16 v[230:231], v188 offset:0xa00
	v_mfma_f32_32x32x16_bf16 v[2:17], v[216:219], v[232:235], v[2:17]
	v_max3_f32 v224, v224, v88, v89
	v_max3_f32 v224, v224, v90, v91
	v_max3_f32 v224, v224, v92, v93
	v_max3_f32 v224, v224, v94, v95
	v_max3_f32 v224, v224, v96, v97
	ds_read_b64_tr_b16 v[232:233], v188 offset:0x1200
	ds_read_b64_tr_b16 v[234:235], v188 offset:0x1a00
	v_mfma_f32_32x32x16_bf16 v[2:17], v[220:223], v[236:239], v[2:17]
	v_max3_f32 v224, v224, v66, v67
	v_max3_f32 v224, v224, v68, v69
	v_max3_f32 v224, v224, v70, v71
	v_max3_f32 v224, v224, v72, v73
	v_max3_f32 v224, v224, v74, v75
	ds_read_b64_tr_b16 v[236:237], v188 offset:0x2200
	ds_read_b64_tr_b16 v[238:239], v188 offset:0x2a00
	ds_read_b64_tr_b16 v[244:245], v188 offset:0x3200
	ds_read_b64_tr_b16 v[246:247], v188 offset:0x3a00
	s_waitcnt lgkmcnt(0)
	v_mfma_f32_32x32x16_bf16 v[2:17], v[248:251], v[240:243], v[2:17]
	v_max3_f32 v224, v224, v76, v77
	v_max3_f32 v224, v224, v78, v79
	v_max3_f32 v224, v224, v80, v81
	v_mov_b32_e32 v225, v224
	s_nop 1
	v_mfma_f32_32x32x16_bf16 v[18:33], v[212:215], v[228:231], v[18:33]
	v_permlane32_swap_b32_e32 v224, v225
	v_max_f32_e32 v225, v225, v225
	v_max_f32_e32 v224, v224, v224
	v_max_f32_e32 v224, v224, v225
	v_max_f32_e32 v226, v164, v164
	ds_read_b64_tr_b16 v[228:229], v188 offset:0x400
	ds_read_b64_tr_b16 v[230:231], v188 offset:0xc00
	v_mfma_f32_32x32x16_bf16 v[18:33], v[216:219], v[232:235], v[18:33]
	v_sub_f32_e32 v225, v224, v164
	v_max_f32_e32 v224, v226, v224
	v_sub_f32_e32 v226, v164, v224
	v_mul_f32_e32 v226, 0x3e0293ee, v226
	v_exp_f32_e32 v226, v226
	ds_read_b64_tr_b16 v[232:233], v188 offset:0x1400
	ds_read_b64_tr_b16 v[234:235], v188 offset:0x1c00
	v_mfma_f32_32x32x16_bf16 v[18:33], v[220:223], v[236:239], v[18:33]
	v_cmp_ge_f32_e32 vcc, s48, v225
	s_cmp_eq_u64 vcc, exec
	s_cselect_b64 s[4:5], -1, 0
	ds_read_b64_tr_b16 v[236:237], v188 offset:0x2400
	ds_read_b64_tr_b16 v[238:239], v188 offset:0x2c00
	ds_read_b64_tr_b16 v[240:241], v188 offset:0x3400
	ds_read_b64_tr_b16 v[242:243], v188 offset:0x3c00
	s_waitcnt lgkmcnt(0)
	v_mfma_f32_32x32x16_bf16 v[18:33], v[248:251], v[244:247], v[18:33]
	v_cndmask_b32_e64 v225, v226, 1.0, s[4:5]
	v_cndmask_b32_e64 v227, v224, v164, s[4:5]
	v_mul_f32_e32 v224, 0xbe0293ee, v227
	v_mfma_f32_32x32x16_bf16 v[50:65], v[212:215], v[228:231], v[50:65]
	v_fmamk_f32 v82, v82, 0x3e0293ee, v224
	v_fmamk_f32 v83, v83, 0x3e0293ee, v224
	v_fmamk_f32 v84, v84, 0x3e0293ee, v224
	ds_read_b64_tr_b16 v[228:229], v188 offset:0x600
	ds_read_b64_tr_b16 v[230:231], v188 offset:0xe00
	v_mfma_f32_32x32x16_bf16 v[50:65], v[216:219], v[232:235], v[50:65]
	v_fmamk_f32 v85, v85, 0x3e0293ee, v224
	v_fmamk_f32 v86, v86, 0x3e0293ee, v224
	v_fmamk_f32 v87, v87, 0x3e0293ee, v224
	ds_read_b64_tr_b16 v[232:233], v188 offset:0x1600
	ds_read_b64_tr_b16 v[234:235], v188 offset:0x1e00
	v_mfma_f32_32x32x16_bf16 v[50:65], v[220:223], v[236:239], v[50:65]
	v_fmamk_f32 v88, v88, 0x3e0293ee, v224
	v_fmamk_f32 v89, v89, 0x3e0293ee, v224
	ds_read_b64_tr_b16 v[236:237], v188 offset:0x2600
	ds_read_b64_tr_b16 v[238:239], v188 offset:0x2e00
	ds_read_b64_tr_b16 v[244:245], v188 offset:0x3600
	ds_read_b64_tr_b16 v[246:247], v188 offset:0x3e00
	s_waitcnt lgkmcnt(0)
	v_mfma_f32_32x32x16_bf16 v[50:65], v[248:251], v[240:243], v[50:65]
	v_fmamk_f32 v90, v90, 0x3e0293ee, v224
	v_fmamk_f32 v91, v91, 0x3e0293ee, v224
	v_mfma_f32_32x32x16_bf16 v[34:49], v[212:215], v[228:231], v[34:49]
	v_fmamk_f32 v92, v92, 0x3e0293ee, v224
	v_fmamk_f32 v93, v93, 0x3e0293ee, v224
	v_mfma_f32_32x32x16_bf16 v[34:49], v[216:219], v[232:235], v[34:49]
	v_fmamk_f32 v94, v94, 0x3e0293ee, v224
	v_fmamk_f32 v95, v95, 0x3e0293ee, v224
	v_mfma_f32_32x32x16_bf16 v[34:49], v[220:223], v[236:239], v[34:49]
	v_fmamk_f32 v96, v96, 0x3e0293ee, v224
	v_fmamk_f32 v97, v97, 0x3e0293ee, v224
	v_mfma_f32_32x32x16_bf16 v[34:49], v[248:251], v[244:247], v[34:49]
	s_barrier
; #define SWAIT() do { if constexpr (SDEPTH == 2) asm volatile("s_waitcnt vmcnt(4)" ::: "memory"); else asm volatile("s_waitcnt vmcnt(0)" ::: "memory"); } while (0)
; #define RESC(a) do { if (__any((a) < 1.f)) { if (hi == 0) al_l[r32] = (a); asm volatile("s_waitcnt lgkmcnt(0)" ::: "memory"); \
;     for (int d = 0; d < 4; ++d) for (int r = 0; r < 16; ++r) o[d][r] *= al_l[crow(r, hi)]; } } while (0)
; template <typename TQ>
; __device__ __forceinline__ void attn_dense_body(const TQ* __restrict__ Qb, const bf16* __restrict__ Kh, const bf16* __restrict__ Vh,
;                                                 unsigned short* __restrict__ Ob, int seq, char* lds) {
;     ...
;     __syncthreads(); SWAIT(); SWRITE(1, SO);
;     RESC(alA); __syncthreads();
	s_waitcnt vmcnt(4)
	v_mov_b32_e32 v162, v225
	v_mov_b32_e32 v208, v227
	v_cmp_gt_f32_e32 vcc, 1.0, v162
	s_waitcnt vmcnt(7)
	ds_write_b128 v191, v[146:149] offset:16384
	s_waitcnt vmcnt(6)
	ds_write_b128 v192, v[150:153] offset:16384
	s_waitcnt vmcnt(5)
	ds_write_b128 v193, v[154:157] offset:49152
	s_waitcnt vmcnt(4)
	ds_write_b128 v194, v[158:161] offset:49152
	s_cbranch_vccz .LBB0_1594
	s_and_saveexec_b64 s[42:43], s[2:3]
	ds_write_b32 v187, v162 offset:128
	s_or_b64 exec, exec, s[42:43]
	s_waitcnt lgkmcnt(0)
	v_add_u32_e32 v158, v182, v186
	ds_read_b128 v[146:149], v158 offset:224
	ds_read_b128 v[150:153], v158 offset:192
	ds_read_b128 v[154:157], v158 offset:160
	ds_read_b128 v[158:161], v158 offset:128
	s_waitcnt lgkmcnt(3)
	v_pk_mul_f32 v[14:15], v[14:15], v[146:147]
	s_waitcnt lgkmcnt(2)
	v_pk_mul_f32 v[10:11], v[10:11], v[150:151]
	s_waitcnt lgkmcnt(1)
	v_pk_mul_f32 v[6:7], v[6:7], v[154:155]
	v_pk_mul_f32 v[16:17], v[16:17], v[148:149]
	v_pk_mul_f32 v[12:13], v[12:13], v[152:153]
	v_pk_mul_f32 v[8:9], v[8:9], v[156:157]
	s_waitcnt lgkmcnt(0)
	v_pk_mul_f32 v[4:5], v[4:5], v[160:161]
	v_pk_mul_f32 v[2:3], v[2:3], v[158:159]
	v_pk_mul_f32 v[30:31], v[30:31], v[146:147]
	v_pk_mul_f32 v[26:27], v[26:27], v[150:151]
	v_pk_mul_f32 v[22:23], v[22:23], v[154:155]
	v_pk_mul_f32 v[32:33], v[32:33], v[148:149]
	v_pk_mul_f32 v[28:29], v[28:29], v[152:153]
	v_pk_mul_f32 v[24:25], v[24:25], v[156:157]
	v_pk_mul_f32 v[20:21], v[20:21], v[160:161]
	v_pk_mul_f32 v[18:19], v[18:19], v[158:159]
	v_pk_mul_f32 v[62:63], v[62:63], v[146:147]
	v_pk_mul_f32 v[58:59], v[58:59], v[150:151]
	v_pk_mul_f32 v[54:55], v[54:55], v[154:155]
	v_pk_mul_f32 v[64:65], v[64:65], v[148:149]
	v_pk_mul_f32 v[60:61], v[60:61], v[152:153]
	v_pk_mul_f32 v[56:57], v[56:57], v[156:157]
	v_pk_mul_f32 v[52:53], v[52:53], v[160:161]
	v_pk_mul_f32 v[50:51], v[50:51], v[158:159]
	v_pk_mul_f32 v[46:47], v[46:47], v[146:147]
	v_pk_mul_f32 v[42:43], v[42:43], v[150:151]
	v_pk_mul_f32 v[38:39], v[38:39], v[154:155]
	v_pk_mul_f32 v[48:49], v[48:49], v[148:149]
	v_pk_mul_f32 v[44:45], v[44:45], v[152:153]
	v_pk_mul_f32 v[40:41], v[40:41], v[156:157]
	v_pk_mul_f32 v[36:37], v[36:37], v[160:161]
	v_pk_mul_f32 v[34:35], v[34:35], v[158:159]
